# nt cache policy on the once-read f32 K/V cache loads of sample attention
# speedup vs baseline: 1.0245x; 1.0006x over previous
.LBB0_849:
	s_ashr_i32 s59, s58, 31
	s_lshl_b64 s[40:41], s[58:59], 19
	s_or_b64 s[40:41], s[40:41], s[48:49]
	s_lshl_b64 s[62:63], s[40:41], 2
	s_waitcnt lgkmcnt(0)
	s_add_u32 s40, s64, s62
	s_addc_u32 s41, s65, s63
	s_add_i32 s58, s67, 0x2000
	s_ashr_i32 s59, s58, 31
	v_lshl_add_u64 v[0:1], s[40:41], 0, v[66:67]
	s_and_b32 s40, s66, 3
	s_lshl_b64 s[64:65], s[58:59], 12
	s_lshl_b32 s40, s40, 10
	s_or_b32 s64, s64, s40
	v_mov_b32_e32 v4, 0
	v_lshl_add_u64 v[28:29], v[0:1], 0, v[64:65]
	v_lshl_add_u64 v[30:31], v[70:71], 0, s[64:65]
	s_mov_b64 s[64:65], 0
	v_mov_b32_e32 v34, v90
	v_mov_b32_e32 v5, v4
	v_mov_b32_e32 v6, v4
	v_mov_b32_e32 v7, v4
	v_mov_b32_e32 v0, v4
	v_mov_b32_e32 v1, v4
	v_mov_b32_e32 v2, v4
	v_mov_b32_e32 v3, v4
	s_and_b64 vcc, exec, s[14:15]
	s_cbranch_vccnz .LBB0_851
	s_mov_b64 s[40:41], 0x20000
	v_lshl_add_u64 v[222:223], v[28:29], 0, s[40:41]
	global_load_dwordx4 v[122:125], v[28:29], off nt
	global_load_dwordx4 v[126:129], v[28:29], off offset:16 nt
	global_load_dwordx4 v[130:133], v[222:223], off nt
	global_load_dwordx4 v[134:137], v[222:223], off offset:16 nt
	global_load_dwordx4 v[138:141], v[28:29], off offset:128 nt
	global_load_dwordx4 v[142:145], v[28:29], off offset:144 nt
	global_load_dwordx4 v[146:149], v[222:223], off offset:128 nt
	global_load_dwordx4 v[150:153], v[222:223], off offset:144 nt
	global_load_dwordx4 v[166:169], v[28:29], off offset:256 nt
	global_load_dwordx4 v[170:173], v[28:29], off offset:272 nt
	global_load_dwordx4 v[174:177], v[222:223], off offset:256 nt
	global_load_dwordx4 v[178:181], v[222:223], off offset:272 nt
	global_load_dwordx4 v[198:201], v[28:29], off offset:384 nt
	global_load_dwordx4 v[202:205], v[28:29], off offset:400 nt
	global_load_dwordx4 v[206:209], v[222:223], off offset:384 nt
	global_load_dwordx4 v[210:213], v[222:223], off offset:400 nt
	ds_read_b128 v[214:217], v34
	ds_read_b128 v[218:221], v34 offset:64
	s_waitcnt vmcnt(12)
	s_waitcnt lgkmcnt(1)
	v_cndmask_b32_e64 v214, v214, 0, s[8:9]
	v_cndmask_b32_e64 v215, v215, 0, s[8:9]
	v_cndmask_b32_e64 v216, v216, 0, s[8:9]
	v_cndmask_b32_e64 v217, v217, 0, s[8:9]
	v_cvt_pk_bf16_f32 v122, v122, v123
	v_cvt_pk_bf16_f32 v123, v124, v125
	v_cvt_pk_bf16_f32 v124, v126, v127
	v_cvt_pk_bf16_f32 v125, v128, v129
	v_cvt_pk_bf16_f32 v130, v130, v131
	v_cvt_pk_bf16_f32 v131, v132, v133
	v_cvt_pk_bf16_f32 v132, v134, v135
	v_cvt_pk_bf16_f32 v133, v136, v137
	v_mfma_f32_16x16x32_bf16 v[4:7], v[122:125], v[214:217], v[4:7]
	s_nop 0
	v_mfma_f32_16x16x32_bf16 v[0:3], v[130:133], v[214:217], v[0:3]
	global_load_dwordx4 v[122:125], v[28:29], off offset:512 nt
	global_load_dwordx4 v[126:129], v[28:29], off offset:528 nt
	global_load_dwordx4 v[130:133], v[222:223], off offset:512 nt
	global_load_dwordx4 v[134:137], v[222:223], off offset:528 nt
	ds_read_b128 v[214:217], v34 offset:128
	s_waitcnt vmcnt(12)
	s_waitcnt lgkmcnt(1)
	v_cndmask_b32_e64 v218, v218, 0, s[8:9]
	v_cndmask_b32_e64 v219, v219, 0, s[8:9]
	v_cndmask_b32_e64 v220, v220, 0, s[8:9]
	v_cndmask_b32_e64 v221, v221, 0, s[8:9]
	v_cvt_pk_bf16_f32 v138, v138, v139
	v_cvt_pk_bf16_f32 v139, v140, v141
	v_cvt_pk_bf16_f32 v140, v142, v143
	v_cvt_pk_bf16_f32 v141, v144, v145
	v_cvt_pk_bf16_f32 v146, v146, v147
	v_cvt_pk_bf16_f32 v147, v148, v149
	v_cvt_pk_bf16_f32 v148, v150, v151
	v_cvt_pk_bf16_f32 v149, v152, v153
	v_mfma_f32_16x16x32_bf16 v[4:7], v[138:141], v[218:221], v[4:7]
	s_nop 0
	v_mfma_f32_16x16x32_bf16 v[0:3], v[146:149], v[218:221], v[0:3]
	global_load_dwordx4 v[138:141], v[28:29], off offset:640 nt
	global_load_dwordx4 v[142:145], v[28:29], off offset:656 nt
	global_load_dwordx4 v[146:149], v[222:223], off offset:640 nt
	global_load_dwordx4 v[150:153], v[222:223], off offset:656 nt
	ds_read_b128 v[218:221], v34 offset:192
	s_waitcnt vmcnt(12)
	s_waitcnt lgkmcnt(1)
	v_cndmask_b32_e64 v214, v214, 0, s[8:9]
	v_cndmask_b32_e64 v215, v215, 0, s[8:9]
	v_cndmask_b32_e64 v216, v216, 0, s[8:9]
	v_cndmask_b32_e64 v217, v217, 0, s[8:9]
	v_cvt_pk_bf16_f32 v166, v166, v167
	v_cvt_pk_bf16_f32 v167, v168, v169
	v_cvt_pk_bf16_f32 v168, v170, v171
	v_cvt_pk_bf16_f32 v169, v172, v173
	v_cvt_pk_bf16_f32 v174, v174, v175
	v_cvt_pk_bf16_f32 v175, v176, v177
	v_cvt_pk_bf16_f32 v176, v178, v179
	v_cvt_pk_bf16_f32 v177, v180, v181
	v_mfma_f32_16x16x32_bf16 v[4:7], v[166:169], v[214:217], v[4:7]
	s_nop 0
	v_mfma_f32_16x16x32_bf16 v[0:3], v[174:177], v[214:217], v[0:3]
	global_load_dwordx4 v[166:169], v[28:29], off offset:768 nt
	global_load_dwordx4 v[170:173], v[28:29], off offset:784 nt
	global_load_dwordx4 v[174:177], v[222:223], off offset:768 nt
	global_load_dwordx4 v[178:181], v[222:223], off offset:784 nt
	ds_read_b128 v[214:217], v34 offset:256
	s_waitcnt vmcnt(12)
	s_waitcnt lgkmcnt(1)
	v_cndmask_b32_e64 v218, v218, 0, s[8:9]
	v_cndmask_b32_e64 v219, v219, 0, s[8:9]
	v_cndmask_b32_e64 v220, v220, 0, s[8:9]
	v_cndmask_b32_e64 v221, v221, 0, s[8:9]
	v_cvt_pk_bf16_f32 v198, v198, v199
	v_cvt_pk_bf16_f32 v199, v200, v201
	v_cvt_pk_bf16_f32 v200, v202, v203
	v_cvt_pk_bf16_f32 v201, v204, v205
	v_cvt_pk_bf16_f32 v206, v206, v207
	v_cvt_pk_bf16_f32 v207, v208, v209
	v_cvt_pk_bf16_f32 v208, v210, v211
	v_cvt_pk_bf16_f32 v209, v212, v213
	v_mfma_f32_16x16x32_bf16 v[4:7], v[198:201], v[218:221], v[4:7]
	s_nop 0
	v_mfma_f32_16x16x32_bf16 v[0:3], v[206:209], v[218:221], v[0:3]
	global_load_dwordx4 v[198:201], v[28:29], off offset:896 nt
	global_load_dwordx4 v[202:205], v[28:29], off offset:912 nt
	global_load_dwordx4 v[206:209], v[222:223], off offset:896 nt
	global_load_dwordx4 v[210:213], v[222:223], off offset:912 nt
	ds_read_b128 v[218:221], v34 offset:320
	s_waitcnt vmcnt(12)
	s_waitcnt lgkmcnt(1)
	v_cndmask_b32_e64 v214, v214, 0, s[8:9]
	v_cndmask_b32_e64 v215, v215, 0, s[8:9]
	v_cndmask_b32_e64 v216, v216, 0, s[8:9]
	v_cndmask_b32_e64 v217, v217, 0, s[8:9]
	v_cvt_pk_bf16_f32 v122, v122, v123
	v_cvt_pk_bf16_f32 v123, v124, v125
	v_cvt_pk_bf16_f32 v124, v126, v127
	v_cvt_pk_bf16_f32 v125, v128, v129
	v_cvt_pk_bf16_f32 v130, v130, v131
	v_cvt_pk_bf16_f32 v131, v132, v133
	v_cvt_pk_bf16_f32 v132, v134, v135
	v_cvt_pk_bf16_f32 v133, v136, v137
	v_mfma_f32_16x16x32_bf16 v[4:7], v[122:125], v[214:217], v[4:7]
	s_nop 0
	v_mfma_f32_16x16x32_bf16 v[0:3], v[130:133], v[214:217], v[0:3]
	global_load_dwordx4 v[122:125], v[28:29], off offset:1024 nt
	global_load_dwordx4 v[126:129], v[28:29], off offset:1040 nt
	global_load_dwordx4 v[130:133], v[222:223], off offset:1024 nt
	global_load_dwordx4 v[134:137], v[222:223], off offset:1040 nt
	ds_read_b128 v[214:217], v34 offset:384
	s_waitcnt vmcnt(12)
	s_waitcnt lgkmcnt(1)
	v_cndmask_b32_e64 v218, v218, 0, s[8:9]
	v_cndmask_b32_e64 v219, v219, 0, s[8:9]
	v_cndmask_b32_e64 v220, v220, 0, s[8:9]
	v_cndmask_b32_e64 v221, v221, 0, s[8:9]
	v_cvt_pk_bf16_f32 v138, v138, v139
	v_cvt_pk_bf16_f32 v139, v140, v141
	v_cvt_pk_bf16_f32 v140, v142, v143
	v_cvt_pk_bf16_f32 v141, v144, v145
	v_cvt_pk_bf16_f32 v146, v146, v147
	v_cvt_pk_bf16_f32 v147, v148, v149
	v_cvt_pk_bf16_f32 v148, v150, v151
	v_cvt_pk_bf16_f32 v149, v152, v153
	v_mfma_f32_16x16x32_bf16 v[4:7], v[138:141], v[218:221], v[4:7]
	s_nop 0
	v_mfma_f32_16x16x32_bf16 v[0:3], v[146:149], v[218:221], v[0:3]
	global_load_dwordx4 v[138:141], v[28:29], off offset:1152 nt
	global_load_dwordx4 v[142:145], v[28:29], off offset:1168 nt
	global_load_dwordx4 v[146:149], v[222:223], off offset:1152 nt
	global_load_dwordx4 v[150:153], v[222:223], off offset:1168 nt
	ds_read_b128 v[218:221], v34 offset:448
	s_waitcnt vmcnt(12)
	s_waitcnt lgkmcnt(1)
	v_cndmask_b32_e64 v214, v214, 0, s[8:9]
	v_cndmask_b32_e64 v215, v215, 0, s[8:9]
	v_cndmask_b32_e64 v216, v216, 0, s[8:9]
	v_cndmask_b32_e64 v217, v217, 0, s[8:9]
	v_cvt_pk_bf16_f32 v166, v166, v167
	v_cvt_pk_bf16_f32 v167, v168, v169
	v_cvt_pk_bf16_f32 v168, v170, v171
	v_cvt_pk_bf16_f32 v169, v172, v173
	v_cvt_pk_bf16_f32 v174, v174, v175
	v_cvt_pk_bf16_f32 v175, v176, v177
	v_cvt_pk_bf16_f32 v176, v178, v179
	v_cvt_pk_bf16_f32 v177, v180, v181
	v_mfma_f32_16x16x32_bf16 v[4:7], v[166:169], v[214:217], v[4:7]
	s_nop 0
	v_mfma_f32_16x16x32_bf16 v[0:3], v[174:177], v[214:217], v[0:3]
	global_load_dwordx4 v[166:169], v[28:29], off offset:1280 nt
	global_load_dwordx4 v[170:173], v[28:29], off offset:1296 nt
	global_load_dwordx4 v[174:177], v[222:223], off offset:1280 nt
	global_load_dwordx4 v[178:181], v[222:223], off offset:1296 nt
	ds_read_b128 v[214:217], v34 offset:512
	s_waitcnt vmcnt(12)
	s_waitcnt lgkmcnt(1)
	v_cndmask_b32_e64 v218, v218, 0, s[8:9]
	v_cndmask_b32_e64 v219, v219, 0, s[8:9]
	v_cndmask_b32_e64 v220, v220, 0, s[8:9]
	v_cndmask_b32_e64 v221, v221, 0, s[8:9]
	v_cvt_pk_bf16_f32 v198, v198, v199
	v_cvt_pk_bf16_f32 v199, v200, v201
	v_cvt_pk_bf16_f32 v200, v202, v203
	v_cvt_pk_bf16_f32 v201, v204, v205
	v_cvt_pk_bf16_f32 v206, v206, v207
	v_cvt_pk_bf16_f32 v207, v208, v209
	v_cvt_pk_bf16_f32 v208, v210, v211
	v_cvt_pk_bf16_f32 v209, v212, v213
	v_mfma_f32_16x16x32_bf16 v[4:7], v[198:201], v[218:221], v[4:7]
	s_nop 0
	v_mfma_f32_16x16x32_bf16 v[0:3], v[206:209], v[218:221], v[0:3]
	global_load_dwordx4 v[198:201], v[28:29], off offset:1408 nt
	global_load_dwordx4 v[202:205], v[28:29], off offset:1424 nt
	global_load_dwordx4 v[206:209], v[222:223], off offset:1408 nt
	global_load_dwordx4 v[210:213], v[222:223], off offset:1424 nt
	ds_read_b128 v[218:221], v34 offset:576
	s_waitcnt vmcnt(12)
	s_waitcnt lgkmcnt(1)
	v_cndmask_b32_e64 v214, v214, 0, s[8:9]
	v_cndmask_b32_e64 v215, v215, 0, s[8:9]
	v_cndmask_b32_e64 v216, v216, 0, s[8:9]
	v_cndmask_b32_e64 v217, v217, 0, s[8:9]
	v_cvt_pk_bf16_f32 v122, v122, v123
	v_cvt_pk_bf16_f32 v123, v124, v125
	v_cvt_pk_bf16_f32 v124, v126, v127
	v_cvt_pk_bf16_f32 v125, v128, v129
	v_cvt_pk_bf16_f32 v130, v130, v131
	v_cvt_pk_bf16_f32 v131, v132, v133
	v_cvt_pk_bf16_f32 v132, v134, v135
	v_cvt_pk_bf16_f32 v133, v136, v137
	v_mfma_f32_16x16x32_bf16 v[4:7], v[122:125], v[214:217], v[4:7]
	s_nop 0
	v_mfma_f32_16x16x32_bf16 v[0:3], v[130:133], v[214:217], v[0:3]
	global_load_dwordx4 v[122:125], v[28:29], off offset:1536 nt
	global_load_dwordx4 v[126:129], v[28:29], off offset:1552 nt
	global_load_dwordx4 v[130:133], v[222:223], off offset:1536 nt
	global_load_dwordx4 v[134:137], v[222:223], off offset:1552 nt
	ds_read_b128 v[214:217], v34 offset:640
	s_waitcnt vmcnt(12)
	s_waitcnt lgkmcnt(1)
	v_cndmask_b32_e64 v218, v218, 0, s[8:9]
	v_cndmask_b32_e64 v219, v219, 0, s[8:9]
	v_cndmask_b32_e64 v220, v220, 0, s[8:9]
	v_cndmask_b32_e64 v221, v221, 0, s[8:9]
	v_cvt_pk_bf16_f32 v138, v138, v139
	v_cvt_pk_bf16_f32 v139, v140, v141
	v_cvt_pk_bf16_f32 v140, v142, v143
	v_cvt_pk_bf16_f32 v141, v144, v145
	v_cvt_pk_bf16_f32 v146, v146, v147
	v_cvt_pk_bf16_f32 v147, v148, v149
	v_cvt_pk_bf16_f32 v148, v150, v151
	v_cvt_pk_bf16_f32 v149, v152, v153
	v_mfma_f32_16x16x32_bf16 v[4:7], v[138:141], v[218:221], v[4:7]
	s_nop 0
	v_mfma_f32_16x16x32_bf16 v[0:3], v[146:149], v[218:221], v[0:3]
	global_load_dwordx4 v[138:141], v[28:29], off offset:1664 nt
	global_load_dwordx4 v[142:145], v[28:29], off offset:1680 nt
	global_load_dwordx4 v[146:149], v[222:223], off offset:1664 nt
	global_load_dwordx4 v[150:153], v[222:223], off offset:1680 nt
	ds_read_b128 v[218:221], v34 offset:704
	s_waitcnt vmcnt(12)
	s_waitcnt lgkmcnt(1)
	v_cndmask_b32_e64 v214, v214, 0, s[8:9]
	v_cndmask_b32_e64 v215, v215, 0, s[8:9]
	v_cndmask_b32_e64 v216, v216, 0, s[8:9]
	v_cndmask_b32_e64 v217, v217, 0, s[8:9]
	v_cvt_pk_bf16_f32 v166, v166, v167
	v_cvt_pk_bf16_f32 v167, v168, v169
	v_cvt_pk_bf16_f32 v168, v170, v171
	v_cvt_pk_bf16_f32 v169, v172, v173
	v_cvt_pk_bf16_f32 v174, v174, v175
	v_cvt_pk_bf16_f32 v175, v176, v177
	v_cvt_pk_bf16_f32 v176, v178, v179
	v_cvt_pk_bf16_f32 v177, v180, v181
	v_mfma_f32_16x16x32_bf16 v[4:7], v[166:169], v[214:217], v[4:7]
	s_nop 0
	v_mfma_f32_16x16x32_bf16 v[0:3], v[174:177], v[214:217], v[0:3]
	global_load_dwordx4 v[166:169], v[28:29], off offset:1792 nt
	global_load_dwordx4 v[170:173], v[28:29], off offset:1808 nt
	global_load_dwordx4 v[174:177], v[222:223], off offset:1792 nt
	global_load_dwordx4 v[178:181], v[222:223], off offset:1808 nt
	ds_read_b128 v[214:217], v34 offset:768
	s_waitcnt vmcnt(12)
	s_waitcnt lgkmcnt(1)
	v_cndmask_b32_e64 v218, v218, 0, s[8:9]
	v_cndmask_b32_e64 v219, v219, 0, s[8:9]
	v_cndmask_b32_e64 v220, v220, 0, s[8:9]
	v_cndmask_b32_e64 v221, v221, 0, s[8:9]
	v_cvt_pk_bf16_f32 v198, v198, v199
	v_cvt_pk_bf16_f32 v199, v200, v201
	v_cvt_pk_bf16_f32 v200, v202, v203
	v_cvt_pk_bf16_f32 v201, v204, v205
	v_cvt_pk_bf16_f32 v206, v206, v207
	v_cvt_pk_bf16_f32 v207, v208, v209
	v_cvt_pk_bf16_f32 v208, v210, v211
	v_cvt_pk_bf16_f32 v209, v212, v213
	v_mfma_f32_16x16x32_bf16 v[4:7], v[198:201], v[218:221], v[4:7]
	s_nop 0
	v_mfma_f32_16x16x32_bf16 v[0:3], v[206:209], v[218:221], v[0:3]
	global_load_dwordx4 v[198:201], v[28:29], off offset:1920 nt
	global_load_dwordx4 v[202:205], v[28:29], off offset:1936 nt
	global_load_dwordx4 v[206:209], v[222:223], off offset:1920 nt
	global_load_dwordx4 v[210:213], v[222:223], off offset:1936 nt
	ds_read_b128 v[218:221], v34 offset:832
	s_waitcnt vmcnt(12)
	s_waitcnt lgkmcnt(1)
	v_cndmask_b32_e64 v214, v214, 0, s[8:9]
	v_cndmask_b32_e64 v215, v215, 0, s[8:9]
	v_cndmask_b32_e64 v216, v216, 0, s[8:9]
	v_cndmask_b32_e64 v217, v217, 0, s[8:9]
	v_cvt_pk_bf16_f32 v122, v122, v123
	v_cvt_pk_bf16_f32 v123, v124, v125
	v_cvt_pk_bf16_f32 v124, v126, v127
	v_cvt_pk_bf16_f32 v125, v128, v129
	v_cvt_pk_bf16_f32 v130, v130, v131
	v_cvt_pk_bf16_f32 v131, v132, v133
	v_cvt_pk_bf16_f32 v132, v134, v135
	v_cvt_pk_bf16_f32 v133, v136, v137
	v_mfma_f32_16x16x32_bf16 v[4:7], v[122:125], v[214:217], v[4:7]
	s_nop 0
	v_mfma_f32_16x16x32_bf16 v[0:3], v[130:133], v[214:217], v[0:3]
	ds_read_b128 v[214:217], v34 offset:896
	s_waitcnt vmcnt(8)
	s_waitcnt lgkmcnt(1)
	v_cndmask_b32_e64 v218, v218, 0, s[8:9]
	v_cndmask_b32_e64 v219, v219, 0, s[8:9]
	v_cndmask_b32_e64 v220, v220, 0, s[8:9]
	v_cndmask_b32_e64 v221, v221, 0, s[8:9]
	v_cvt_pk_bf16_f32 v138, v138, v139
	v_cvt_pk_bf16_f32 v139, v140, v141
	v_cvt_pk_bf16_f32 v140, v142, v143
	v_cvt_pk_bf16_f32 v141, v144, v145
	v_cvt_pk_bf16_f32 v146, v146, v147
	v_cvt_pk_bf16_f32 v147, v148, v149
	v_cvt_pk_bf16_f32 v148, v150, v151
	v_cvt_pk_bf16_f32 v149, v152, v153
	v_mfma_f32_16x16x32_bf16 v[4:7], v[138:141], v[218:221], v[4:7]
	s_nop 0
	v_mfma_f32_16x16x32_bf16 v[0:3], v[146:149], v[218:221], v[0:3]
	ds_read_b128 v[218:221], v34 offset:960
	s_waitcnt vmcnt(4)
	s_waitcnt lgkmcnt(1)
	v_cndmask_b32_e64 v214, v214, 0, s[8:9]
	v_cndmask_b32_e64 v215, v215, 0, s[8:9]
	v_cndmask_b32_e64 v216, v216, 0, s[8:9]
	v_cndmask_b32_e64 v217, v217, 0, s[8:9]
	v_cvt_pk_bf16_f32 v166, v166, v167
	v_cvt_pk_bf16_f32 v167, v168, v169
	v_cvt_pk_bf16_f32 v168, v170, v171
	v_cvt_pk_bf16_f32 v169, v172, v173
	v_cvt_pk_bf16_f32 v174, v174, v175
	v_cvt_pk_bf16_f32 v175, v176, v177
	v_cvt_pk_bf16_f32 v176, v178, v179
	v_cvt_pk_bf16_f32 v177, v180, v181
	v_mfma_f32_16x16x32_bf16 v[4:7], v[166:169], v[214:217], v[4:7]
	s_nop 0
	v_mfma_f32_16x16x32_bf16 v[0:3], v[174:177], v[214:217], v[0:3]
	s_waitcnt vmcnt(0)
	s_waitcnt lgkmcnt(0)
	v_cndmask_b32_e64 v218, v218, 0, s[8:9]
	v_cndmask_b32_e64 v219, v219, 0, s[8:9]
	v_cndmask_b32_e64 v220, v220, 0, s[8:9]
	v_cndmask_b32_e64 v221, v221, 0, s[8:9]
	v_cvt_pk_bf16_f32 v198, v198, v199
	v_cvt_pk_bf16_f32 v199, v200, v201
	v_cvt_pk_bf16_f32 v200, v202, v203
	v_cvt_pk_bf16_f32 v201, v204, v205
	v_cvt_pk_bf16_f32 v206, v206, v207
	v_cvt_pk_bf16_f32 v207, v208, v209
	v_cvt_pk_bf16_f32 v208, v210, v211
	v_cvt_pk_bf16_f32 v209, v212, v213
	v_mfma_f32_16x16x32_bf16 v[4:7], v[198:201], v[218:221], v[4:7]
	s_nop 0
	v_mfma_f32_16x16x32_bf16 v[0:3], v[206:209], v[218:221], v[0:3]
	s_nop 7
	s_branch .LBB0_883

.LBB0_886:
	v_lshl_add_u64 v[80:81], v[78:79], 0, s[60:61]
	s_movk_i32 s40, 0x2000
	v_add_co_u32_e32 v20, vcc, s40, v80
	ds_read_b128 v[12:15], v73
	s_nop 0
	v_addc_co_u32_e32 v21, vcc, 0, v81, vcc
	v_add_co_u32_e32 v22, vcc, s29, v80
	s_add_u32 s60, s60, 0x100000
	s_nop 0
	v_addc_co_u32_e32 v23, vcc, 0, v81, vcc
	v_add_co_u32_e32 v24, vcc, s55, v80
	s_addc_u32 s61, s61, 0
	s_nop 0
	v_addc_co_u32_e32 v25, vcc, 0, v81, vcc
	v_add_co_u32_e32 v26, vcc, s68, v80
	s_cmp_eq_u32 s60, 0x200000
	s_nop 0
	v_addc_co_u32_e32 v27, vcc, 0, v81, vcc
	v_add_co_u32_e32 v28, vcc, s69, v80
	s_nop 1
	v_addc_co_u32_e32 v29, vcc, 0, v81, vcc
	v_add_co_u32_e32 v30, vcc, s70, v80
	s_nop 1
	v_addc_co_u32_e32 v31, vcc, 0, v81, vcc
	v_add_co_u32_e32 v32, vcc, s71, v80
	s_nop 1
	v_addc_co_u32_e32 v33, vcc, 0, v81, vcc
	global_load_dwordx4 v[34:37], v[80:81], off nt
	global_load_dwordx4 v[38:41], v[20:21], off nt
	s_nop 0
	global_load_dwordx4 v[20:23], v[22:23], off nt
	s_nop 0
	global_load_dwordx4 v[50:53], v[24:25], off nt
	s_nop 0
	global_load_dwordx4 v[24:27], v[26:27], off nt
	s_nop 0
	global_load_dwordx4 v[54:57], v[28:29], off nt
	s_nop 0
	global_load_dwordx4 v[28:31], v[30:31], off nt
	s_nop 0
	global_load_dwordx4 v[58:61], v[32:33], off nt
	v_add_co_u32_e32 v62, vcc, s72, v80
	s_waitcnt vmcnt(6)
	v_cvt_pk_bf16_f32 v94, v34, v38
	s_nop 0
	v_addc_co_u32_e32 v63, vcc, 0, v81, vcc
	v_add_co_u32_e32 v102, vcc, s73, v80
	s_waitcnt vmcnt(4)
	v_cvt_pk_bf16_f32 v95, v20, v50
	s_waitcnt vmcnt(2)
	v_cvt_pk_bf16_f32 v96, v24, v54
	s_waitcnt vmcnt(0)
	v_cvt_pk_bf16_f32 v97, v28, v58
	v_cvt_pk_bf16_f32 v48, v35, v39
	v_addc_co_u32_e32 v103, vcc, 0, v81, vcc
	v_add_co_u32_e32 v106, vcc, s74, v80
	v_cvt_pk_bf16_f32 v49, v21, v51
	v_cvt_pk_bf16_f32 v50, v25, v55
	v_cvt_pk_bf16_f32 v51, v29, v59
	v_cvt_pk_bf16_f32 v44, v36, v40
	s_nop 1
	v_addc_co_u32_e32 v107, vcc, 0, v81, vcc
	v_add_co_u32_e32 v110, vcc, s75, v80
	v_cvt_pk_bf16_f32 v45, v22, v52
	v_cvt_pk_bf16_f32 v46, v26, v56
	v_cvt_pk_bf16_f32 v47, v30, v60
	v_cvt_pk_bf16_f32 v40, v37, v41
	s_nop 1
	v_addc_co_u32_e32 v111, vcc, 0, v81, vcc
	v_add_co_u32_e32 v114, vcc, s81, v80
	v_cvt_pk_bf16_f32 v41, v23, v53
	v_cvt_pk_bf16_f32 v42, v27, v57
	v_cvt_pk_bf16_f32 v43, v31, v61
	s_waitcnt lgkmcnt(0)
	v_mfma_f32_16x16x32_bf16 v[16:19], v[94:97], v[12:15], v[16:19]
	v_addc_co_u32_e32 v115, vcc, 0, v81, vcc
	v_add_co_u32_e32 v116, vcc, s82, v80
	v_mfma_f32_16x16x32_bf16 v[8:11], v[48:51], v[12:15], v[8:11]
	s_nop 0
	v_addc_co_u32_e32 v117, vcc, 0, v81, vcc
	v_add_co_u32_e32 v118, vcc, s83, v80
	v_mfma_f32_16x16x32_bf16 v[4:7], v[44:47], v[12:15], v[4:7]
	s_nop 0
	v_addc_co_u32_e32 v119, vcc, 0, v81, vcc
	v_add_co_u32_e32 v120, vcc, s84, v80
	v_mfma_f32_16x16x32_bf16 v[0:3], v[40:43], v[12:15], v[0:3]
	s_nop 0
	v_addc_co_u32_e32 v121, vcc, 0, v81, vcc
	global_load_dwordx4 v[98:101], v[62:63], off nt
	s_nop 0
	global_load_dwordx4 v[102:105], v[102:103], off nt
	s_nop 0
	global_load_dwordx4 v[106:109], v[106:107], off nt
	s_nop 0
	global_load_dwordx4 v[110:113], v[110:111], off nt
	s_nop 0
	global_load_dwordx4 v[24:27], v[114:115], off nt
	global_load_dwordx4 v[52:55], v[116:117], off nt
	global_load_dwordx4 v[56:59], v[118:119], off nt
	global_load_dwordx4 v[60:63], v[120:121], off nt
	v_add_co_u32_e32 v82, vcc, s85, v80
	ds_read_b128 v[20:23], v73 offset:64
	s_nop 0
	v_addc_co_u32_e32 v83, vcc, 0, v81, vcc
	s_waitcnt vmcnt(6)
	v_cvt_pk_bf16_f32 v36, v98, v102
	s_waitcnt vmcnt(4)
	v_cvt_pk_bf16_f32 v37, v106, v110
	s_waitcnt vmcnt(2)
	v_cvt_pk_bf16_f32 v38, v24, v52
	v_add_co_u32_e32 v52, vcc, s86, v80
	s_waitcnt vmcnt(0)
	v_cvt_pk_bf16_f32 v39, v56, v60
	v_cvt_pk_bf16_f32 v32, v99, v103
	v_cvt_pk_bf16_f32 v33, v107, v111
	v_cvt_pk_bf16_f32 v34, v25, v53
	s_nop 0
	v_addc_co_u32_e32 v53, vcc, 0, v81, vcc
	v_add_co_u32_e32 v56, vcc, s87, v80
	v_cvt_pk_bf16_f32 v35, v57, v61
	v_cvt_pk_bf16_f32 v28, v100, v104
	v_cvt_pk_bf16_f32 v29, v108, v112
	v_cvt_pk_bf16_f32 v30, v26, v54
	s_nop 1
	v_addc_co_u32_e32 v57, vcc, 0, v81, vcc
	v_add_co_u32_e32 v60, vcc, s88, v80
	v_cvt_pk_bf16_f32 v31, v58, v62
	v_cvt_pk_bf16_f32 v24, v101, v105
	v_cvt_pk_bf16_f32 v25, v109, v113
	v_cvt_pk_bf16_f32 v26, v27, v55
	s_nop 1
	v_addc_co_u32_e32 v61, vcc, 0, v81, vcc
	v_add_co_u32_e32 v98, vcc, s89, v80
	v_cvt_pk_bf16_f32 v27, v59, v63
	s_waitcnt lgkmcnt(0)
	v_mfma_f32_16x16x32_bf16 v[12:15], v[36:39], v[20:23], v[16:19]
	v_addc_co_u32_e32 v99, vcc, 0, v81, vcc
	v_add_co_u32_e32 v102, vcc, s90, v80
	v_mfma_f32_16x16x32_bf16 v[8:11], v[32:35], v[20:23], v[8:11]
	s_nop 0
	v_addc_co_u32_e32 v103, vcc, 0, v81, vcc
	v_add_co_u32_e32 v106, vcc, s91, v80
	v_mfma_f32_16x16x32_bf16 v[4:7], v[28:31], v[20:23], v[4:7]
	s_nop 0
	v_addc_co_u32_e32 v107, vcc, 0, v81, vcc
	v_add_co_u32_e32 v110, vcc, s92, v80
	v_mfma_f32_16x16x32_bf16 v[0:3], v[24:27], v[20:23], v[0:3]
	s_nop 0
	v_addc_co_u32_e32 v111, vcc, 0, v81, vcc
	global_load_dwordx4 v[94:97], v[82:83], off nt
	s_nop 0
	global_load_dwordx4 v[52:55], v[52:53], off nt
	s_nop 0
	global_load_dwordx4 v[56:59], v[56:57], off nt
	s_nop 0
	global_load_dwordx4 v[60:63], v[60:61], off nt
	s_nop 0
	global_load_dwordx4 v[98:101], v[98:99], off nt
	s_nop 0
	global_load_dwordx4 v[102:105], v[102:103], off nt
	s_nop 0
	global_load_dwordx4 v[106:109], v[106:107], off nt
	s_nop 0
	global_load_dwordx4 v[110:113], v[110:111], off nt
	v_add_co_u32_e32 v114, vcc, s93, v80
	ds_read_b128 v[16:19], v73 offset:128
	s_nop 0
	v_addc_co_u32_e32 v115, vcc, 0, v81, vcc
	v_add_co_u32_e32 v48, vcc, s94, v80
	s_waitcnt vmcnt(6)
	v_cvt_pk_bf16_f32 v20, v94, v52
	s_nop 0
	v_addc_co_u32_e32 v49, vcc, 0, v81, vcc
	v_add_co_u32_e32 v50, vcc, s95, v80
	s_waitcnt vmcnt(4)
	v_cvt_pk_bf16_f32 v21, v56, v60
	s_waitcnt vmcnt(2)
	v_cvt_pk_bf16_f32 v22, v98, v102
	s_waitcnt vmcnt(0)
	v_cvt_pk_bf16_f32 v23, v106, v110
	v_cvt_pk_bf16_f32 v24, v95, v53
	v_addc_co_u32_e32 v51, vcc, 0, v81, vcc
	v_add_co_u32_e32 v44, vcc, s96, v80
	v_cvt_pk_bf16_f32 v25, v57, v61
	v_cvt_pk_bf16_f32 v26, v99, v103
	v_cvt_pk_bf16_f32 v27, v107, v111
	v_cvt_pk_bf16_f32 v28, v96, v54
	s_nop 1
	v_addc_co_u32_e32 v45, vcc, 0, v81, vcc
	v_add_co_u32_e32 v82, vcc, s97, v80
	v_cvt_pk_bf16_f32 v29, v58, v62
	v_cvt_pk_bf16_f32 v30, v100, v104
	v_cvt_pk_bf16_f32 v31, v108, v112
	v_cvt_pk_bf16_f32 v32, v97, v55
	s_nop 1
	v_addc_co_u32_e32 v83, vcc, 0, v81, vcc
	v_add_co_u32_e32 v116, vcc, s76, v80
	v_cvt_pk_bf16_f32 v33, v59, v63
	v_cvt_pk_bf16_f32 v34, v101, v105
	v_cvt_pk_bf16_f32 v35, v109, v113
	global_load_dwordx4 v[36:39], v[114:115], off nt
	s_nop 0
	v_addc_co_u32_e32 v117, vcc, 0, v81, vcc
	v_add_co_u32_e32 v118, vcc, s3, v80
	s_waitcnt lgkmcnt(0)
	v_mfma_f32_16x16x32_bf16 v[12:15], v[20:23], v[16:19], v[12:15]
	v_addc_co_u32_e32 v119, vcc, 0, v81, vcc
	global_load_dwordx4 v[20:23], v[48:49], off nt
	global_load_dwordx4 v[40:43], v[50:51], off nt
	s_nop 0
	global_load_dwordx4 v[44:47], v[44:45], off nt
	v_mfma_f32_16x16x32_bf16 v[8:11], v[24:27], v[16:19], v[8:11]
	global_load_dwordx4 v[24:27], v[82:83], off nt
	global_load_dwordx4 v[48:51], v[116:117], off nt
	global_load_dwordx4 v[52:55], v[118:119], off nt
	ds_read_b128 v[56:59], v73 offset:192
	v_add_co_u32_e32 v80, vcc, s79, v80
	v_mfma_f32_16x16x32_bf16 v[4:7], v[28:31], v[16:19], v[4:7]
	s_nop 0
	v_addc_co_u32_e32 v81, vcc, 0, v81, vcc
	global_load_dwordx4 v[28:31], v[80:81], off nt
	v_mfma_f32_16x16x32_bf16 v[0:3], v[32:35], v[16:19], v[0:3]
	s_waitcnt vmcnt(6)
	v_cvt_pk_bf16_f32 v16, v36, v20
	s_waitcnt vmcnt(4)
	v_cvt_pk_bf16_f32 v17, v40, v44
	s_waitcnt vmcnt(2)
	v_cvt_pk_bf16_f32 v18, v24, v48
	s_waitcnt vmcnt(0)
	v_cvt_pk_bf16_f32 v19, v52, v28
	v_cvt_pk_bf16_f32 v32, v37, v21
	v_cvt_pk_bf16_f32 v33, v41, v45
	v_cvt_pk_bf16_f32 v34, v25, v49
	v_cvt_pk_bf16_f32 v35, v53, v29
	v_add_u32_e32 v73, 0x100, v73
	s_waitcnt lgkmcnt(0)
	v_mfma_f32_16x16x32_bf16 v[16:19], v[16:19], v[56:59], v[12:15]
	v_cvt_pk_bf16_f32 v12, v38, v22
	v_cvt_pk_bf16_f32 v13, v42, v46
	v_cvt_pk_bf16_f32 v14, v26, v50
	v_mfma_f32_16x16x32_bf16 v[8:11], v[32:35], v[56:59], v[8:11]
	v_cvt_pk_bf16_f32 v15, v54, v30
	v_cvt_pk_bf16_f32 v20, v39, v23
	v_cvt_pk_bf16_f32 v21, v43, v47
	v_cvt_pk_bf16_f32 v22, v27, v51
	v_cvt_pk_bf16_f32 v23, v55, v31
	s_nop 0
	v_mfma_f32_16x16x32_bf16 v[4:7], v[12:15], v[56:59], v[4:7]
	v_mfma_f32_16x16x32_bf16 v[0:3], v[20:23], v[56:59], v[0:3]
	s_cbranch_scc0 .LBB0_886
	s_and_saveexec_b64 s[60:61], s[12:13]
	s_cbranch_execz .LBB0_842
	v_or_b32_e32 v12, s58, v84
	v_ashrrev_i32_e32 v13, 31, v12
	v_lshlrev_b64 v[12:13], 12, v[12:13]
	v_lshl_add_u64 v[12:13], s[44:45], 0, v[12:13]
	s_lshl_b32 s48, s48, 1
	v_lshl_add_u64 v[12:13], v[12:13], 0, s[48:49]
	v_lshl_add_u64 v[12:13], s[52:53], 1, v[12:13]
	v_mov_b32_e32 v77, v65
	v_lshl_add_u64 v[20:21], v[12:13], 0, v[76:77]
	v_cvt_pk_bf16_f32 v12, v16, v8
	v_cvt_pk_bf16_f32 v13, v4, v0
	v_cvt_pk_bf16_f32 v14, v17, v9
	v_cvt_pk_bf16_f32 v15, v5, v1
	v_cvt_pk_bf16_f32 v0, v18, v10
	v_cvt_pk_bf16_f32 v1, v6, v2
	v_cvt_pk_bf16_f32 v2, v19, v11
	v_cvt_pk_bf16_f32 v3, v7, v3
	flat_store_dwordx4 v[20:21], v[12:15]
	flat_store_dwordx4 v[20:21], v[0:3] offset:16
	s_branch .LBB0_842
